# best + accumulator zeroing between GEMM units with packed 64-bit moves (64 instead of 128 VALU ops) in the two main unit loops
# speedup vs baseline: 1.0036x; 1.0036x over previous
; template <class Epi, class Sched, bool ALIGN_EPI = false, bool SP2 = false>
; __device__ __forceinline__ void gemm_phase(PG8_LAS unsigned char* lds, const Gemm g, const Sched& S, const Epi& E) {
;     ...
; #pragma unroll
;         for (int a = 0; a < 2; ++a)
; #pragma unroll
;             for (int b = 0; b < 2; ++b)
; #pragma unroll
;                 for (int m = 0; m < 4; ++m)
; #pragma unroll
;                     for (int n = 0; n < 2; ++n) acc[a][b][m][n] = (f32x4){0.f, 0.f, 0.f, 0.f};
;         cur = nxt; cA = nA; cB = nB; ++ui;
.LBB0_328:
	v_mov_b32_e32 v0, 0
	s_mov_b32 s62, s26
	s_mov_b32 s63, s27
	s_mov_b64 s[16:17], s[46:47]
	s_mov_b64 s[14:15], s[44:45]
	s_mov_b32 s80, s28
	v_mov_b32_e32 v1, v0
	v_pk_mov_b32 v[2:3], v[0:1], v[0:1]
	v_pk_mov_b32 v[4:5], v[0:1], v[0:1]
	v_pk_mov_b32 v[6:7], v[0:1], v[0:1]
	v_pk_mov_b32 v[8:9], v[0:1], v[0:1]
	v_pk_mov_b32 v[10:11], v[0:1], v[0:1]
	v_pk_mov_b32 v[12:13], v[0:1], v[0:1]
	v_pk_mov_b32 v[14:15], v[0:1], v[0:1]
	v_pk_mov_b32 v[16:17], v[0:1], v[0:1]
	v_pk_mov_b32 v[18:19], v[0:1], v[0:1]
	v_pk_mov_b32 v[20:21], v[0:1], v[0:1]
	v_pk_mov_b32 v[22:23], v[0:1], v[0:1]
	v_pk_mov_b32 v[24:25], v[0:1], v[0:1]
	v_pk_mov_b32 v[26:27], v[0:1], v[0:1]
	v_pk_mov_b32 v[28:29], v[0:1], v[0:1]
	v_pk_mov_b32 v[30:31], v[0:1], v[0:1]
	v_pk_mov_b32 v[32:33], v[0:1], v[0:1]
	v_pk_mov_b32 v[34:35], v[0:1], v[0:1]
	v_pk_mov_b32 v[36:37], v[0:1], v[0:1]
	v_pk_mov_b32 v[38:39], v[0:1], v[0:1]
	v_pk_mov_b32 v[40:41], v[0:1], v[0:1]
	v_pk_mov_b32 v[42:43], v[0:1], v[0:1]
	v_pk_mov_b32 v[44:45], v[0:1], v[0:1]
	v_pk_mov_b32 v[46:47], v[0:1], v[0:1]
	v_pk_mov_b32 v[48:49], v[0:1], v[0:1]
	v_pk_mov_b32 v[50:51], v[0:1], v[0:1]
	v_pk_mov_b32 v[52:53], v[0:1], v[0:1]
	v_pk_mov_b32 v[54:55], v[0:1], v[0:1]
	v_pk_mov_b32 v[56:57], v[0:1], v[0:1]
	v_pk_mov_b32 v[58:59], v[0:1], v[0:1]
	v_pk_mov_b32 v[60:61], v[0:1], v[0:1]
	v_pk_mov_b32 v[62:63], v[0:1], v[0:1]
	v_pk_mov_b32 v[64:65], v[0:1], v[0:1]
	v_pk_mov_b32 v[66:67], v[0:1], v[0:1]
	v_pk_mov_b32 v[68:69], v[0:1], v[0:1]
	v_pk_mov_b32 v[70:71], v[0:1], v[0:1]
	v_pk_mov_b32 v[72:73], v[0:1], v[0:1]
	v_pk_mov_b32 v[74:75], v[0:1], v[0:1]
	v_pk_mov_b32 v[76:77], v[0:1], v[0:1]
	v_pk_mov_b32 v[78:79], v[0:1], v[0:1]
	v_pk_mov_b32 v[80:81], v[0:1], v[0:1]
	v_pk_mov_b32 v[82:83], v[0:1], v[0:1]
	v_pk_mov_b32 v[84:85], v[0:1], v[0:1]
	v_pk_mov_b32 v[86:87], v[0:1], v[0:1]
	v_pk_mov_b32 v[88:89], v[0:1], v[0:1]
	v_pk_mov_b32 v[90:91], v[0:1], v[0:1]
	v_pk_mov_b32 v[92:93], v[0:1], v[0:1]
	v_pk_mov_b32 v[94:95], v[0:1], v[0:1]
	v_pk_mov_b32 v[96:97], v[0:1], v[0:1]
	v_pk_mov_b32 v[98:99], v[0:1], v[0:1]
	v_pk_mov_b32 v[100:101], v[0:1], v[0:1]
	v_pk_mov_b32 v[102:103], v[0:1], v[0:1]
	v_pk_mov_b32 v[104:105], v[0:1], v[0:1]
	v_pk_mov_b32 v[106:107], v[0:1], v[0:1]
	v_pk_mov_b32 v[108:109], v[0:1], v[0:1]
	v_pk_mov_b32 v[110:111], v[0:1], v[0:1]
	v_pk_mov_b32 v[112:113], v[0:1], v[0:1]
	v_pk_mov_b32 v[114:115], v[0:1], v[0:1]
	v_pk_mov_b32 v[116:117], v[0:1], v[0:1]
	v_pk_mov_b32 v[118:119], v[0:1], v[0:1]
	v_pk_mov_b32 v[120:121], v[0:1], v[0:1]
	v_pk_mov_b32 v[122:123], v[0:1], v[0:1]
	v_pk_mov_b32 v[124:125], v[0:1], v[0:1]
	v_pk_mov_b32 v[126:127], v[0:1], v[0:1]

; #define PG8_BAR __builtin_amdgcn_s_barrier()
; template <class Epi, class Sched, bool ALIGN_EPI = false, bool SP2 = false>
; __device__ __forceinline__ void gemm_phase(PG8_LAS unsigned char* lds, const Gemm g, const Sched& S, const Epi& E) {
;     ...
; #pragma unroll
;         for (int a = 0; a < 2; ++a)
; #pragma unroll
;             for (int b = 0; b < 2; ++b)
; #pragma unroll
;                 for (int m = 0; m < 4; ++m)
; #pragma unroll
;                     for (int n = 0; n < 2; ++n) acc[a][b][m][n] = (f32x4){0.f, 0.f, 0.f, 0.f};
;         cur = nxt; cA = nA; cB = nB; ++ui;
;         if constexpr (ALIGN_EPI) { if (wr == 1) PG8_BAR; }
.LBB0_418:
	v_mov_b32_e32 v0, 0
	s_mov_b32 s14, s44
	s_mov_b32 s16, s46
	v_mov_b32_e32 v1, v0
	v_pk_mov_b32 v[2:3], v[0:1], v[0:1]
	v_pk_mov_b32 v[4:5], v[0:1], v[0:1]
	v_pk_mov_b32 v[6:7], v[0:1], v[0:1]
	v_pk_mov_b32 v[8:9], v[0:1], v[0:1]
	v_pk_mov_b32 v[10:11], v[0:1], v[0:1]
	v_pk_mov_b32 v[12:13], v[0:1], v[0:1]
	v_pk_mov_b32 v[14:15], v[0:1], v[0:1]
	v_pk_mov_b32 v[16:17], v[0:1], v[0:1]
	v_pk_mov_b32 v[18:19], v[0:1], v[0:1]
	v_pk_mov_b32 v[20:21], v[0:1], v[0:1]
	v_pk_mov_b32 v[22:23], v[0:1], v[0:1]
	v_pk_mov_b32 v[24:25], v[0:1], v[0:1]
	v_pk_mov_b32 v[26:27], v[0:1], v[0:1]
	v_pk_mov_b32 v[28:29], v[0:1], v[0:1]
	v_pk_mov_b32 v[30:31], v[0:1], v[0:1]
	v_pk_mov_b32 v[32:33], v[0:1], v[0:1]
	v_pk_mov_b32 v[34:35], v[0:1], v[0:1]
	v_pk_mov_b32 v[36:37], v[0:1], v[0:1]
	v_pk_mov_b32 v[38:39], v[0:1], v[0:1]
	v_pk_mov_b32 v[40:41], v[0:1], v[0:1]
	v_pk_mov_b32 v[42:43], v[0:1], v[0:1]
	v_pk_mov_b32 v[44:45], v[0:1], v[0:1]
	v_pk_mov_b32 v[46:47], v[0:1], v[0:1]
	v_pk_mov_b32 v[48:49], v[0:1], v[0:1]
	v_pk_mov_b32 v[50:51], v[0:1], v[0:1]
	v_pk_mov_b32 v[52:53], v[0:1], v[0:1]
	v_pk_mov_b32 v[54:55], v[0:1], v[0:1]
	v_pk_mov_b32 v[56:57], v[0:1], v[0:1]
	v_pk_mov_b32 v[58:59], v[0:1], v[0:1]
	v_pk_mov_b32 v[60:61], v[0:1], v[0:1]
	v_pk_mov_b32 v[62:63], v[0:1], v[0:1]
	v_pk_mov_b32 v[64:65], v[0:1], v[0:1]
	v_pk_mov_b32 v[66:67], v[0:1], v[0:1]
	v_pk_mov_b32 v[68:69], v[0:1], v[0:1]
	v_pk_mov_b32 v[70:71], v[0:1], v[0:1]
	v_pk_mov_b32 v[72:73], v[0:1], v[0:1]
	v_pk_mov_b32 v[74:75], v[0:1], v[0:1]
	v_pk_mov_b32 v[76:77], v[0:1], v[0:1]
	v_pk_mov_b32 v[78:79], v[0:1], v[0:1]
	v_pk_mov_b32 v[80:81], v[0:1], v[0:1]
	v_pk_mov_b32 v[82:83], v[0:1], v[0:1]
	v_pk_mov_b32 v[84:85], v[0:1], v[0:1]
	v_pk_mov_b32 v[86:87], v[0:1], v[0:1]
	v_pk_mov_b32 v[88:89], v[0:1], v[0:1]
	v_pk_mov_b32 v[90:91], v[0:1], v[0:1]
	v_pk_mov_b32 v[92:93], v[0:1], v[0:1]
	v_pk_mov_b32 v[94:95], v[0:1], v[0:1]
	v_pk_mov_b32 v[96:97], v[0:1], v[0:1]
	v_pk_mov_b32 v[98:99], v[0:1], v[0:1]
	v_pk_mov_b32 v[100:101], v[0:1], v[0:1]
	v_pk_mov_b32 v[102:103], v[0:1], v[0:1]
	v_pk_mov_b32 v[104:105], v[0:1], v[0:1]
	v_pk_mov_b32 v[106:107], v[0:1], v[0:1]
	v_pk_mov_b32 v[108:109], v[0:1], v[0:1]
	v_pk_mov_b32 v[110:111], v[0:1], v[0:1]
	v_pk_mov_b32 v[112:113], v[0:1], v[0:1]
	v_pk_mov_b32 v[114:115], v[0:1], v[0:1]
	v_pk_mov_b32 v[116:117], v[0:1], v[0:1]
	v_pk_mov_b32 v[118:119], v[0:1], v[0:1]
	v_pk_mov_b32 v[120:121], v[0:1], v[0:1]
	v_pk_mov_b32 v[122:123], v[0:1], v[0:1]
	v_pk_mov_b32 v[124:125], v[0:1], v[0:1]
	v_pk_mov_b32 v[126:127], v[0:1], v[0:1]
	s_mov_b64 s[42:43], s[50:51]
	s_mov_b32 s72, s28
	s_andn2_b64 vcc, exec, s[38:39]
	s_mov_b64 s[52:53], s[48:49]
	s_cbranch_vccz .LBB0_442
